# removed the vmcnt(0) drain in front of the three residual (EpiResid) epilogues: the unused look-ahead tile loads now drain under the epilogue
# speedup vs baseline: 1.0017x; 1.0017x over previous
; __device__ __forceinline__ unsigned pk2(float lo, float hi) { f32x2_t v = {lo, hi}; bf16x2_t b = __builtin_convertvector(v, bf16x2_t); return __builtin_bit_cast(unsigned, b); }
; __device__ __forceinline__ float shx(float v, int mask, int lane) { return __int_as_float(__builtin_amdgcn_ds_bpermute((lane ^ mask) << 2, __float_as_int(v))); }
;     __device__ __forceinline__ void operator()(EPI_ARGS) const {
;     ...
;                 int row = EPI_ROWS(ai, m); asm volatile("" : "+v"(row));
; #pragma unroll
;                 for (int bj = 0; bj < 2; ++bj) {
;                     const size_t off = (size_t)row * D + u.pn * 256 + bj * 128 + wc * 32 + 8 * fq;
;                     const f32x4 v0 = acc[ai][bj][m][0], v1 = acc[ai][bj][m][1];
;                     *(f32x4*)(h + off) = v0; *(f32x4*)(h + off + 4) = v1;
;                     u32x4 w; w.x = pk2(v0[0], v0[1]); w.y = pk2(v0[2], v0[3]); w.z = pk2(v1[0], v1[1]); w.w = pk2(v1[2], v1[3]);
;                     *(u32x4*)(HB + off) = w;
;                     float s = (v0[0] * v0[0] + v0[1] * v0[1]) + (v0[2] * v0[2] + v0[3] * v0[3]) + (v1[0] * v1[0] + v1[1] * v1[1]) + (v1[2] * v1[2] + v1[3] * v1[3]);
;                     s += shx(s, 16, fq * 16 + fr); s += shx(s, 32, fq * 16 + fr);
;                     if (fq == 0) SS[(size_t)row * 32 + u.pn * 8 + bj * 4 + wc] = s;
.LBB0_57:
	s_nop 0
	v_mul_f32_e32 v154, v125, v125
	v_mul_f32_e32 v155, v127, v127
	v_fmac_f32_e32 v154, v124, v124
	v_fmac_f32_e32 v155, v126, v126
	v_add_f32_e32 v154, v154, v155
	v_mul_f32_e32 v155, v121, v121
	v_fmac_f32_e32 v155, v120, v120
	s_lshl_b32 s54, s75, 8
	v_add_f32_e32 v154, v155, v154
	v_mul_f32_e32 v155, v123, v123
	v_add_u32_e32 v153, s54, v146
	v_fmac_f32_e32 v155, v122, v122
	v_mov_b32_e32 v142, v153
	v_add_f32_e32 v157, v155, v154
	s_lshl_b32 s50, s64, 8
	v_ashrrev_i32_e32 v143, 31, v142
	ds_bpermute_b32 v160, v150, v157
	v_lshlrev_b64 v[144:145], 10, v[142:143]
	s_ashr_i32 s51, s50, 31
	v_lshl_add_u64 v[144:145], v[144:145], 0, s[50:51]
	v_or_b32_e32 v144, v144, v136
	v_lshlrev_b64 v[158:159], 7, v[142:143]
	v_lshl_add_u64 v[142:143], v[144:145], 2, s[34:35]
	global_store_dwordx4 v[142:143], v[124:127], off
	v_cvt_pk_bf16_f32 v154, v124, v125
	global_store_dwordx4 v[142:143], v[120:123], off offset:16
	s_waitcnt lgkmcnt(0)
	v_add_f32_e32 v124, v157, v160
	ds_bpermute_b32 v125, v151, v124
	v_cvt_pk_bf16_f32 v155, v126, v127
	v_cvt_pk_bf16_f32 v156, v120, v121
	v_cvt_pk_bf16_f32 v157, v122, v123
	v_lshl_add_u64 v[120:121], v[144:145], 1, s[90:91]
	global_store_dwordx4 v[120:121], v[154:157], off
	v_lshl_add_u64 v[120:121], s[94:95], 0, v[158:159]
	s_and_saveexec_b64 s[52:53], s[36:37]
	s_cbranch_execz .LBB0_59
	s_lshl_b32 s56, s64, 3
	s_ashr_i32 s57, s56, 31
	v_lshl_add_u64 v[122:123], s[56:57], 2, v[120:121]
	s_lshl_b32 s56, s29, 2
	s_mov_b32 s57, s5
	v_lshl_add_u64 v[122:123], v[122:123], 0, s[56:57]
	s_waitcnt lgkmcnt(0)
	v_add_f32_e32 v124, v124, v125
	global_store_dword v[122:123], v124, off

; __device__ __forceinline__ unsigned pk2(float lo, float hi) { f32x2_t v = {lo, hi}; bf16x2_t b = __builtin_convertvector(v, bf16x2_t); return __builtin_bit_cast(unsigned, b); }
; __device__ __forceinline__ float shx(float v, int mask, int lane) { return __int_as_float(__builtin_amdgcn_ds_bpermute((lane ^ mask) << 2, __float_as_int(v))); }
;     __device__ __forceinline__ void operator()(EPI_ARGS) const {
;     ...
;                 int row = EPI_ROWS(ai, m); asm volatile("" : "+v"(row));
; #pragma unroll
;                 for (int bj = 0; bj < 2; ++bj) {
;                     const size_t off = (size_t)row * D + u.pn * 256 + bj * 128 + wc * 32 + 8 * fq;
;                     const f32x4 v0 = acc[ai][bj][m][0], v1 = acc[ai][bj][m][1];
;                     *(f32x4*)(h + off) = v0; *(f32x4*)(h + off + 4) = v1;
;                     u32x4 w; w.x = pk2(v0[0], v0[1]); w.y = pk2(v0[2], v0[3]); w.z = pk2(v1[0], v1[1]); w.w = pk2(v1[2], v1[3]);
;                     *(u32x4*)(HB + off) = w;
;                     float s = (v0[0] * v0[0] + v0[1] * v0[1]) + (v0[2] * v0[2] + v0[3] * v0[3]) + (v1[0] * v1[0] + v1[1] * v1[1]) + (v1[2] * v1[2] + v1[3] * v1[3]);
;                     s += shx(s, 16, fq * 16 + fr); s += shx(s, 32, fq * 16 + fr);
;                     if (fq == 0) SS[(size_t)row * 32 + u.pn * 8 + bj * 4 + wc] = s;
.LBB0_126:
	s_nop 0
	v_mul_f32_e32 v154, v125, v125
	v_mul_f32_e32 v155, v127, v127
	v_fmac_f32_e32 v154, v124, v124
	v_fmac_f32_e32 v155, v126, v126
	v_add_f32_e32 v154, v154, v155
	v_mul_f32_e32 v155, v121, v121
	v_fmac_f32_e32 v155, v120, v120
	s_lshl_b32 s45, s74, 8
	v_add_f32_e32 v154, v155, v154
	v_mul_f32_e32 v155, v123, v123
	v_add_u32_e32 v153, s45, v146
	v_fmac_f32_e32 v155, v122, v122
	v_mov_b32_e32 v142, v153
	v_add_f32_e32 v157, v155, v154
	s_lshl_b32 s2, s64, 8
	v_ashrrev_i32_e32 v143, 31, v142
	ds_bpermute_b32 v160, v150, v157
	v_lshlrev_b64 v[144:145], 10, v[142:143]
	s_ashr_i32 s3, s2, 31
	v_lshl_add_u64 v[144:145], v[144:145], 0, s[2:3]
	v_or_b32_e32 v144, v144, v136
	v_lshlrev_b64 v[158:159], 7, v[142:143]
	v_lshl_add_u64 v[142:143], v[144:145], 2, s[34:35]
	global_store_dwordx4 v[142:143], v[124:127], off
	v_cvt_pk_bf16_f32 v154, v124, v125
	global_store_dwordx4 v[142:143], v[120:123], off offset:16
	s_waitcnt lgkmcnt(0)
	v_add_f32_e32 v124, v157, v160
	ds_bpermute_b32 v125, v151, v124
	v_cvt_pk_bf16_f32 v155, v126, v127
	v_cvt_pk_bf16_f32 v156, v120, v121
	v_cvt_pk_bf16_f32 v157, v122, v123
	v_lshl_add_u64 v[120:121], v[144:145], 1, s[90:91]
	global_store_dwordx4 v[120:121], v[154:157], off
	v_lshl_add_u64 v[120:121], s[94:95], 0, v[158:159]
	s_and_saveexec_b64 s[50:51], s[36:37]
	s_cbranch_execz .LBB0_128
	s_lshl_b32 s22, s64, 3
	s_ashr_i32 s23, s22, 31
	v_lshl_add_u64 v[122:123], s[22:23], 2, v[120:121]
	s_lshl_b32 s22, s60, 2
	s_mov_b32 s23, s5
	v_lshl_add_u64 v[122:123], v[122:123], 0, s[22:23]
	s_waitcnt lgkmcnt(0)
	v_add_f32_e32 v124, v124, v125
	global_store_dword v[122:123], v124, off

; __device__ __forceinline__ unsigned pk2(float lo, float hi) { f32x2_t v = {lo, hi}; bf16x2_t b = __builtin_convertvector(v, bf16x2_t); return __builtin_bit_cast(unsigned, b); }
; __device__ __forceinline__ float shx(float v, int mask, int lane) { return __int_as_float(__builtin_amdgcn_ds_bpermute((lane ^ mask) << 2, __float_as_int(v))); }
;     __device__ __forceinline__ void operator()(EPI_ARGS) const {
;     ...
;                 int row = EPI_ROWS(ai, m); asm volatile("" : "+v"(row));
; #pragma unroll
;                 for (int bj = 0; bj < 2; ++bj) {
;                     const size_t off = (size_t)row * D + u.pn * 256 + bj * 128 + wc * 32 + 8 * fq;
;                     const f32x4 v0 = acc[ai][bj][m][0], v1 = acc[ai][bj][m][1];
;                     *(f32x4*)(h + off) = v0; *(f32x4*)(h + off + 4) = v1;
;                     u32x4 w; w.x = pk2(v0[0], v0[1]); w.y = pk2(v0[2], v0[3]); w.z = pk2(v1[0], v1[1]); w.w = pk2(v1[2], v1[3]);
;                     *(u32x4*)(HB + off) = w;
;                     float s = (v0[0] * v0[0] + v0[1] * v0[1]) + (v0[2] * v0[2] + v0[3] * v0[3]) + (v1[0] * v1[0] + v1[1] * v1[1]) + (v1[2] * v1[2] + v1[3] * v1[3]);
;                     s += shx(s, 16, fq * 16 + fr); s += shx(s, 32, fq * 16 + fr);
;                     if (fq == 0) SS[(size_t)row * 32 + u.pn * 8 + bj * 4 + wc] = s;
.LBB0_623:
	s_nop 0
	v_mul_f32_e32 v154, v125, v125
	v_mul_f32_e32 v155, v127, v127
	v_fmac_f32_e32 v154, v124, v124
	v_fmac_f32_e32 v155, v126, v126
	v_add_f32_e32 v154, v154, v155
	v_mul_f32_e32 v155, v121, v121
	v_fmac_f32_e32 v155, v120, v120
	s_lshl_b32 s43, s70, 8
	v_add_f32_e32 v154, v155, v154
	v_mul_f32_e32 v155, v123, v123
	v_add_u32_e32 v153, s43, v146
	v_fmac_f32_e32 v155, v122, v122
	v_mov_b32_e32 v142, v153
	v_add_f32_e32 v157, v155, v154
	s_lshl_b32 s48, s62, 8
	v_ashrrev_i32_e32 v143, 31, v142
	ds_bpermute_b32 v160, v150, v157
	v_lshlrev_b64 v[144:145], 10, v[142:143]
	s_ashr_i32 s49, s48, 31
	v_lshl_add_u64 v[144:145], v[144:145], 0, s[48:49]
	v_or_b32_e32 v144, v144, v136
	v_lshlrev_b64 v[158:159], 7, v[142:143]
	v_lshl_add_u64 v[142:143], v[144:145], 2, s[34:35]
	global_store_dwordx4 v[142:143], v[124:127], off
	v_cvt_pk_bf16_f32 v154, v124, v125
	global_store_dwordx4 v[142:143], v[120:123], off offset:16
	s_waitcnt lgkmcnt(0)
	v_add_f32_e32 v124, v157, v160
	ds_bpermute_b32 v125, v151, v124
	v_cvt_pk_bf16_f32 v155, v126, v127
	v_cvt_pk_bf16_f32 v156, v120, v121
	v_cvt_pk_bf16_f32 v157, v122, v123
	v_lshl_add_u64 v[120:121], v[144:145], 1, s[90:91]
	global_store_dwordx4 v[120:121], v[154:157], off
	v_lshl_add_u64 v[120:121], s[94:95], 0, v[158:159]
	s_and_saveexec_b64 s[50:51], s[36:37]
	s_cbranch_execz .LBB0_625
	s_lshl_b32 s52, s62, 3
	s_ashr_i32 s53, s52, 31
	v_lshl_add_u64 v[122:123], s[52:53], 2, v[120:121]
	s_lshl_b32 s52, s58, 2
	s_mov_b32 s53, s5
	v_lshl_add_u64 v[122:123], v[122:123], 0, s[52:53]
	s_waitcnt lgkmcnt(0)
	v_add_f32_e32 v124, v124, v125
	global_store_dword v[122:123], v124, off
